# MoBA k-mean pre-pass: 32-step LDS partial-sum reduction issues ds_reads in batches of 8 with counted waits (same add order)
# baseline (speedup 1.0000x reference)
.LBB0_479:
	s_waitcnt vmcnt(3)
	v_lshl_add_u32 v20, s8, 8, v42
	v_or_b32_e32 v6, 1, v20
	v_mad_i64_i32 v[2:3], s[4:5], v20, s3, v[38:39]
	v_mad_i64_i32 v[6:7], s[4:5], v6, s3, v[38:39]
	global_load_dwordx4 v[2:5], v[2:3], off
	v_or_b32_e32 v14, 3, v20
	global_load_dwordx4 v[10:13], v[6:7], off
	v_or_b32_e32 v6, 2, v20
	v_mad_i64_i32 v[6:7], s[4:5], v6, s3, v[38:39]
	v_mad_i64_i32 v[14:15], s[4:5], v14, s3, v[38:39]
	global_load_dwordx4 v[6:9], v[6:7], off
	v_or_b32_e32 v18, 5, v20
	global_load_dwordx4 v[22:25], v[14:15], off
	v_or_b32_e32 v14, 4, v20
	v_mad_i64_i32 v[14:15], s[4:5], v14, s3, v[38:39]
	v_mad_i64_i32 v[18:19], s[4:5], v18, s3, v[38:39]
	global_load_dwordx4 v[14:17], v[14:15], off
	s_waitcnt vmcnt(4)
	v_lshlrev_b32_e32 v34, 16, v2
	global_load_dwordx4 v[30:33], v[18:19], off
	v_or_b32_e32 v18, 6, v20
	v_mad_i64_i32 v[18:19], s[4:5], v18, s3, v[38:39]
	global_load_dwordx4 v[26:29], v[18:19], off
	v_or_b32_e32 v18, 7, v20
	v_mad_i64_i32 v[18:19], s[4:5], v18, s3, v[38:39]
	global_load_dwordx4 v[18:21], v[18:19], off
	v_and_b32_e32 v35, 0xffff0000, v2
	v_lshlrev_b32_e32 v2, 16, v3
	v_and_b32_e32 v3, 0xffff0000, v3
	v_pk_add_f32 v[34:35], v[34:35], 0 op_sel_hi:[1,0]
	s_waitcnt vmcnt(6)
	v_lshlrev_b32_e32 v36, 16, v10
	v_and_b32_e32 v37, 0xffff0000, v10
	v_pk_add_f32 v[2:3], v[2:3], 0 op_sel_hi:[1,0]
	v_lshlrev_b32_e32 v10, 16, v11
	v_and_b32_e32 v11, 0xffff0000, v11
	v_pk_add_f32 v[34:35], v[34:35], v[36:37]
	s_waitcnt vmcnt(5)
	v_lshlrev_b32_e32 v36, 16, v6
	v_and_b32_e32 v37, 0xffff0000, v6
	v_pk_add_f32 v[2:3], v[2:3], v[10:11]
	v_lshlrev_b32_e32 v6, 16, v7
	v_and_b32_e32 v7, 0xffff0000, v7
	v_pk_add_f32 v[34:35], v[34:35], v[36:37]
	s_waitcnt vmcnt(4)
	v_lshlrev_b32_e32 v36, 16, v22
	v_and_b32_e32 v37, 0xffff0000, v22
	v_pk_add_f32 v[2:3], v[2:3], v[6:7]
	v_lshlrev_b32_e32 v6, 16, v23
	v_and_b32_e32 v7, 0xffff0000, v23
	v_pk_add_f32 v[34:35], v[34:35], v[36:37]
	s_waitcnt vmcnt(3)
	v_lshlrev_b32_e32 v36, 16, v14
	v_and_b32_e32 v37, 0xffff0000, v14
	v_pk_add_f32 v[2:3], v[2:3], v[6:7]
	v_lshlrev_b32_e32 v6, 16, v15
	v_and_b32_e32 v7, 0xffff0000, v15
	v_pk_add_f32 v[34:35], v[34:35], v[36:37]
	v_pk_add_f32 v[2:3], v[2:3], v[6:7]
	s_waitcnt vmcnt(2)
	v_lshlrev_b32_e32 v36, 16, v30
	v_and_b32_e32 v37, 0xffff0000, v30
	v_lshlrev_b32_e32 v6, 16, v31
	v_and_b32_e32 v7, 0xffff0000, v31
	v_pk_add_f32 v[34:35], v[34:35], v[36:37]
	s_waitcnt vmcnt(1)
	v_lshlrev_b32_e32 v36, 16, v26
	v_and_b32_e32 v37, 0xffff0000, v26
	v_pk_add_f32 v[2:3], v[2:3], v[6:7]
	v_lshlrev_b32_e32 v6, 16, v27
	v_and_b32_e32 v7, 0xffff0000, v27
	v_pk_add_f32 v[34:35], v[34:35], v[36:37]
	s_waitcnt vmcnt(0)
	v_lshlrev_b32_e32 v36, 16, v18
	v_and_b32_e32 v37, 0xffff0000, v18
	v_pk_add_f32 v[2:3], v[2:3], v[6:7]
	v_lshlrev_b32_e32 v6, 16, v19
	v_and_b32_e32 v7, 0xffff0000, v19
	v_pk_add_f32 v[34:35], v[34:35], v[36:37]
	v_pk_add_f32 v[36:37], v[2:3], v[6:7]
	v_lshlrev_b32_e32 v2, 16, v4
	v_and_b32_e32 v3, 0xffff0000, v4
	v_pk_add_f32 v[2:3], v[2:3], 0 op_sel_hi:[1,0]
	v_lshlrev_b32_e32 v6, 16, v12
	v_and_b32_e32 v7, 0xffff0000, v12
	v_pk_add_f32 v[2:3], v[2:3], v[6:7]
	v_lshlrev_b32_e32 v6, 16, v8
	v_and_b32_e32 v7, 0xffff0000, v8
	v_pk_add_f32 v[2:3], v[2:3], v[6:7]
	v_lshlrev_b32_e32 v6, 16, v24
	v_and_b32_e32 v7, 0xffff0000, v24
	v_pk_add_f32 v[2:3], v[2:3], v[6:7]
	v_lshlrev_b32_e32 v6, 16, v16
	v_and_b32_e32 v7, 0xffff0000, v16
	v_pk_add_f32 v[2:3], v[2:3], v[6:7]
	v_lshlrev_b32_e32 v6, 16, v32
	v_and_b32_e32 v7, 0xffff0000, v32
	v_pk_add_f32 v[2:3], v[2:3], v[6:7]
	v_lshlrev_b32_e32 v6, 16, v28
	v_and_b32_e32 v7, 0xffff0000, v28
	v_pk_add_f32 v[2:3], v[2:3], v[6:7]
	v_lshlrev_b32_e32 v6, 16, v20
	v_and_b32_e32 v7, 0xffff0000, v20
	v_lshlrev_b32_e32 v4, 16, v5
	v_and_b32_e32 v5, 0xffff0000, v5
	v_pk_add_f32 v[2:3], v[2:3], v[6:7]
	v_pk_add_f32 v[4:5], v[4:5], 0 op_sel_hi:[1,0]
	v_lshlrev_b32_e32 v6, 16, v13
	v_and_b32_e32 v7, 0xffff0000, v13
	v_pk_add_f32 v[4:5], v[4:5], v[6:7]
	v_lshlrev_b32_e32 v6, 16, v9
	v_and_b32_e32 v7, 0xffff0000, v9
	v_pk_add_f32 v[4:5], v[4:5], v[6:7]
	v_lshlrev_b32_e32 v6, 16, v25
	v_and_b32_e32 v7, 0xffff0000, v25
	v_pk_add_f32 v[4:5], v[4:5], v[6:7]
	v_lshlrev_b32_e32 v6, 16, v17
	v_and_b32_e32 v7, 0xffff0000, v17
	v_pk_add_f32 v[4:5], v[4:5], v[6:7]
	v_lshlrev_b32_e32 v6, 16, v33
	v_and_b32_e32 v7, 0xffff0000, v33
	v_pk_add_f32 v[4:5], v[4:5], v[6:7]
	v_lshlrev_b32_e32 v6, 16, v29
	v_and_b32_e32 v7, 0xffff0000, v29
	v_pk_add_f32 v[4:5], v[4:5], v[6:7]
	v_lshlrev_b32_e32 v6, 16, v21
	v_and_b32_e32 v7, 0xffff0000, v21
	v_pk_add_f32 v[4:5], v[4:5], v[6:7]
	ds_write_b128 v45, v[34:37]
	ds_write_b128 v45, v[2:5] offset:16
	s_waitcnt lgkmcnt(0)
	s_barrier
	s_and_saveexec_b64 s[4:5], vcc
	s_cbranch_execz .LBB0_478
	v_mov_b32_e32 v2, 0
	v_add_u32_e32 v3, 0x12000, v44
	ds_read_b32 v6, v3
	ds_read_b32 v7, v3 offset:512
	ds_read_b32 v8, v3 offset:1024
	ds_read_b32 v9, v3 offset:1536
	ds_read_b32 v10, v3 offset:2048
	ds_read_b32 v11, v3 offset:2560
	ds_read_b32 v12, v3 offset:3072
	ds_read_b32 v13, v3 offset:3584
	ds_read_b32 v14, v3 offset:4096
	ds_read_b32 v15, v3 offset:4608
	ds_read_b32 v16, v3 offset:5120
	ds_read_b32 v17, v3 offset:5632
	ds_read_b32 v18, v3 offset:6144
	ds_read_b32 v19, v3 offset:6656
	ds_read_b32 v20, v3 offset:7168
	ds_read_b32 v21, v3 offset:7680
	s_waitcnt lgkmcnt(15)
	v_add_f32_e32 v2, v2, v6
	s_waitcnt lgkmcnt(14)
	v_add_f32_e32 v2, v2, v7
	s_waitcnt lgkmcnt(13)
	v_add_f32_e32 v2, v2, v8
	s_waitcnt lgkmcnt(12)
	v_add_f32_e32 v2, v2, v9
	s_waitcnt lgkmcnt(11)
	v_add_f32_e32 v2, v2, v10
	s_waitcnt lgkmcnt(10)
	v_add_f32_e32 v2, v2, v11
	s_waitcnt lgkmcnt(9)
	v_add_f32_e32 v2, v2, v12
	s_waitcnt lgkmcnt(8)
	v_add_f32_e32 v2, v2, v13
	ds_read_b32 v6, v3 offset:8192
	ds_read_b32 v7, v3 offset:8704
	ds_read_b32 v8, v3 offset:9216
	ds_read_b32 v9, v3 offset:9728
	ds_read_b32 v10, v3 offset:10240
	ds_read_b32 v11, v3 offset:10752
	ds_read_b32 v12, v3 offset:11264
	ds_read_b32 v13, v3 offset:11776
	s_waitcnt lgkmcnt(15)
	v_add_f32_e32 v2, v2, v14
	s_waitcnt lgkmcnt(14)
	v_add_f32_e32 v2, v2, v15
	s_waitcnt lgkmcnt(13)
	v_add_f32_e32 v2, v2, v16
	s_waitcnt lgkmcnt(12)
	v_add_f32_e32 v2, v2, v17
	s_waitcnt lgkmcnt(11)
	v_add_f32_e32 v2, v2, v18
	s_waitcnt lgkmcnt(10)
	v_add_f32_e32 v2, v2, v19
	s_waitcnt lgkmcnt(9)
	v_add_f32_e32 v2, v2, v20
	s_waitcnt lgkmcnt(8)
	v_add_f32_e32 v2, v2, v21
	ds_read_b32 v14, v3 offset:12288
	ds_read_b32 v15, v3 offset:12800
	ds_read_b32 v16, v3 offset:13312
	ds_read_b32 v17, v3 offset:13824
	ds_read_b32 v18, v3 offset:14336
	ds_read_b32 v19, v3 offset:14848
	ds_read_b32 v20, v3 offset:15360
	ds_read_b32 v21, v3 offset:15872
	s_waitcnt lgkmcnt(15)
	v_add_f32_e32 v2, v2, v6
	s_waitcnt lgkmcnt(14)
	v_add_f32_e32 v2, v2, v7
	s_waitcnt lgkmcnt(13)
	v_add_f32_e32 v2, v2, v8
	s_waitcnt lgkmcnt(12)
	v_add_f32_e32 v2, v2, v9
	s_waitcnt lgkmcnt(11)
	v_add_f32_e32 v2, v2, v10
	s_waitcnt lgkmcnt(10)
	v_add_f32_e32 v2, v2, v11
	s_waitcnt lgkmcnt(9)
	v_add_f32_e32 v2, v2, v12
	s_waitcnt lgkmcnt(8)
	v_add_f32_e32 v2, v2, v13
	s_waitcnt lgkmcnt(7)
	v_add_f32_e32 v2, v2, v14
	s_waitcnt lgkmcnt(6)
	v_add_f32_e32 v2, v2, v15
	s_waitcnt lgkmcnt(5)
	v_add_f32_e32 v2, v2, v16
	s_waitcnt lgkmcnt(4)
	v_add_f32_e32 v2, v2, v17
	s_waitcnt lgkmcnt(3)
	v_add_f32_e32 v2, v2, v18
	s_waitcnt lgkmcnt(2)
	v_add_f32_e32 v2, v2, v19
	s_waitcnt lgkmcnt(1)
	v_add_f32_e32 v2, v2, v20
	s_waitcnt lgkmcnt(0)
	v_add_f32_e32 v2, v2, v21
	s_movk_i32 s9, 0x4000
	v_mul_f32_e32 v2, 0x3b800000, v2
	v_lshl_add_u32 v3, s8, 9, v43
	ds_write_b32 v3, v2
	s_branch .LBB0_478
